# MLA: static priority on waves 0-3 instead of waves 4-7 (direction check of the priority lever)
# baseline (speedup 1.0000x reference)
; #define SLOAD() do { vs0 = *(const bf16x8*)(Vh + voff); vs1 = *(const bf16x8*)(Vh + voff + 32u * (unsigned)ldv); \
;     ks0 = *(const bf16x8*)(Kh + koff); ks1 = *(const bf16x8*)(Kh + koff + 32u * (unsigned)ldk); \
;     if constexpr (NR > 0) { kr = *(const bf16x8*)(Krh + kroff); kroff += 64u * 64u; } voff += 64u * (unsigned)ldv; koff += 64u * (unsigned)ldk; } while (0)
; #define SWRITE(b) do { *(bf16x8*)(V_lds + (b) * SHM_V + vst0) = vs0; *(bf16x8*)(V_lds + (b) * SHM_V + vst1) = vs1; const int kc = sc * 2;  \
;     *(bf16x8*)(K_lds + (b) * SHM_K + KSWZ(sr, kc)) = ks0; *(bf16x8*)(K_lds + (b) * SHM_K + KSWZ(32 + sr, kc)) = ks1; \
;     if constexpr (NR > 0) *(bf16x8*)(Kr_lds + (b) * SHM_KR + krst) = kr; } while (0)
; __device__ __forceinline__ v8i32 cat8(v4i32 a, v4i32 b) { return (v8i32){a[0], a[1], a[2], a[3], b[0], b[1], b[2], b[3]}; }
; __device__ __forceinline__ void attn_unit7(const unsigned char* __restrict__ Q8, int ldq, const unsigned char* __restrict__ Kn8, int ldk, const unsigned char* __restrict__ Kr8, ...
;   int tid_ = threadIdx.x; asm volatile("" : "+v"(tid_));
;   const int tid = tid_, wid = tid >> 6, lane = tid & 63, r32 = lane & 31, hi = lane >> 5;
;   char* Vt_lds = lds + G8_VT; char* Kn_lds = lds + G8_KN; char* Kr_lds = lds + G8_KR;
;   float* ws = (float*)(lds + G8_WS) + wid * 64; float* li_l = ws; float* al_l = ws + 32;
;   float m_reg = 0.f, l_reg = 0; f32x16 o[4] = {}; v8i32 qf[3];
;   { const unsigned char* Qw = Q8 + (unsigned)((wid * 32 + r32) * ldq + hi * 32);
; #pragma unroll
;     for (int s = 0; s < 3; ++s) qf[s] = cat8(*reinterpret_cast<const v4i32*>(Qw + s * 64), *reinterpret_cast<const v4i32*>(Qw + s * 64 + 16)); }
;   const int vtr = tid >> 2, vtc = tid & 3, vtst = vtr * 64 + ((vtc ^ ((vtr >> 2) & 3)) << 4);
;   const int knr = tid >> 3, knc = tid & 7, knst = KN8SW(knr, knc);
;   const int krr = (tid >> 2) & 63, krc = tid & 3, krst = KR8SW(krr, krc);
;   const bool krw = tid < 256;
;   unsigned vtoff = (unsigned)(tid * 16), knoff = (unsigned)(knr * ldk + knc * 16), kroff = (unsigned)(krr * 64 + krc * 16);
;   v4i32 vt, kn, kr;
;     ...
;   f32x16 pA0, pA1, pB0, pB1; float alA, alB; v8i32 p8;
;   SLOAD(); SWRITE(0); __syncthreads();
;   SLOAD();
;   qkt9(pA0, pA1, Kn_lds, Kr_lds, qf, 7.0f - m_reg, r32, hi); partialSM9(pA0, pA1, m_reg, alA, thr_raw);
;   SWRITE(1); __syncthreads();
.LBB0_1320:
	s_or_b64 exec, exec, s[20:21]
	v_and_b32_e32 v0, 0x3fffffc0, v12
	s_mov_b32 s20, 0x60000
	v_lshl_add_u32 v187, v0, 2, 0
	v_add3_u32 v178, v13, v14, s20
	v_add_u32_e32 v0, v15, v16
	v_mov_b32_e32 v14, v1
	v_mov_b32_e32 v15, v1
	v_and_b32_e32 v184, 63, v12
	v_lshl_add_u64 v[180:181], s[12:13], 0, v[0:1]
	v_mov_b32_e32 v0, v1
	v_mov_b32_e32 v2, v1
	v_mov_b32_e32 v3, v1
	v_mov_b32_e32 v4, v1
	v_mov_b32_e32 v5, v1
	v_mov_b32_e32 v6, v1
	v_mov_b32_e32 v7, v1
	v_mov_b32_e32 v8, v1
	v_mov_b32_e32 v9, v1
	v_mov_b32_e32 v10, v1
	v_mov_b32_e32 v11, v1
	v_mov_b32_e32 v12, v1
	v_mov_b32_e32 v13, v1
	v_mov_b64_e32 v[64:65], v[14:15]
	v_mov_b64_e32 v[48:49], v[14:15]
	v_mov_b64_e32 v[32:33], v[14:15]
	v_mov_b64_e32 v[62:63], v[12:13]
	v_mov_b64_e32 v[60:61], v[10:11]
	v_mov_b64_e32 v[58:59], v[8:9]
	v_mov_b64_e32 v[56:57], v[6:7]
	v_mov_b64_e32 v[54:55], v[4:5]
	v_mov_b64_e32 v[52:53], v[2:3]
	v_mov_b64_e32 v[50:51], v[0:1]
	v_mov_b64_e32 v[46:47], v[12:13]
	v_mov_b64_e32 v[44:45], v[10:11]
	v_mov_b64_e32 v[42:43], v[8:9]
	v_mov_b64_e32 v[40:41], v[6:7]
	v_mov_b64_e32 v[38:39], v[4:5]
	v_mov_b64_e32 v[36:37], v[2:3]
	v_mov_b64_e32 v[34:35], v[0:1]
	v_mov_b64_e32 v[30:31], v[12:13]
	v_mov_b64_e32 v[28:29], v[10:11]
	v_mov_b64_e32 v[26:27], v[8:9]
	v_mov_b64_e32 v[24:25], v[6:7]
	v_mov_b64_e32 v[22:23], v[4:5]
	v_mov_b64_e32 v[20:21], v[2:3]
	v_mov_b64_e32 v[18:19], v[0:1]
	v_mov_b64_e32 v[16:17], v[14:15]
	s_lshl_b32 s29, s29, 8
	v_cmp_gt_u32_e64 s[40:41], 32, v184
	v_lshl_add_u32 v208, v183, 2, v187
	v_lshlrev_b32_e32 v207, 4, v175
	v_add_u32_e32 v176, 0x6000, v174
	v_mov_b32_e32 v209, 0
	s_mov_b32 s30, -1
	v_mov_b64_e32 v[14:15], v[12:13]
	v_mov_b64_e32 v[12:13], v[10:11]
	v_mov_b64_e32 v[10:11], v[8:9]
	v_mov_b64_e32 v[8:9], v[6:7]
	v_mov_b64_e32 v[6:7], v[4:5]
	v_mov_b64_e32 v[4:5], v[2:3]
	v_mov_b64_e32 v[2:3], v[0:1]
	v_add_u32_e32 v176, 0xffffe000, v176
	v_add_u32_e32 v178, 0xfffe0000, v178
	v_sub_f32_e32 v230, 0x40e00000, v217
	v_mov_b32_e32 v231, v230
	v_mov_b32_e32 v232, v230
	v_mov_b32_e32 v233, v230
	v_mov_b32_e32 v234, v230
	v_mov_b32_e32 v235, v230
	v_mov_b32_e32 v236, v230
	v_mov_b32_e32 v237, v230
	v_mov_b32_e32 v238, v230
	v_mov_b32_e32 v239, v230
	v_mov_b32_e32 v240, v230
	v_mov_b32_e32 v241, v230
	v_mov_b32_e32 v242, v230
	v_mov_b32_e32 v243, v230
	v_mov_b32_e32 v244, v230
	v_mov_b32_e32 v245, v230
	s_mov_b32 s30, 0
	v_lshrrev_b32_e32 v222, 4, v189
	v_and_b32_e32 v223, 3, v222
	v_and_b32_e32 v222, 7, v222
	v_lshlrev_b32_e32 v223, 4, v223
	v_lshlrev_b32_e32 v222, 4, v222
	v_xor_b32_e32 v176, v176, v223
	v_xor_b32_e32 v180, v180, v223
	v_xor_b32_e32 v178, v178, v222
	v_lshrrev_b32_e32 v222, 6, v189
	s_nop 0
	v_readfirstlane_b32 s98, v222
	s_nop 3
	s_lshl_b32 s98, s98, 10
	s_waitcnt lgkmcnt(0)
	s_barrier
	s_cmp_eq_u64 s[42:43], 0
	s_cbranch_scc1 .Lmla_stag_entry
	s_setprio 1

; __device__ __forceinline__ void finishSM9(f32x16& p0, f32x16& p1, float alpha, float& l_reg, v8i32& p8) {
; #pragma unroll
;   for (int r = 0; r < 16; ++r) { p0[r] = __builtin_amdgcn_exp2f(p0[r]); p1[r] = __builtin_amdgcn_exp2f(p1[r]); }
;   float ps = 0;
; #pragma unroll
;   for (int r = 0; r < 16; ++r) ps += p0[r];
; #pragma unroll
;   for (int r = 0; r < 16; ++r) ps += p1[r];
;   { auto rr = __builtin_amdgcn_permlane32_swap(__float_as_uint(ps), __float_as_uint(ps), false, false);
;     ps = __uint_as_float(rr[0]) + __uint_as_float(rr[1]); }
;   l_reg = l_reg * alpha + ps;
; #pragma unroll
;   for (int g = 0; g < 4; ++g) {
;     int w = __builtin_amdgcn_cvt_pk_fp8_f32(p0[4 * g], p0[4 * g + 1], 0, false); p8[g] = __builtin_amdgcn_cvt_pk_fp8_f32(p0[4 * g + 2], p0[4 * g + 3], w, true);
;     int u = __builtin_amdgcn_cvt_pk_fp8_f32(p1[4 * g], p1[4 * g + 1], 0, false); p8[4 + g] = __builtin_amdgcn_cvt_pk_fp8_f32(p1[4 * g + 2], p1[4 * g + 3], u, true); }
; }
; __device__ __forceinline__ void pv8(f32x16* o, const char* Vt, const v8i32 p8, int r32, int hi) {
;   const int sw = (r32 >> 2) & 3, a0 = r32 * 64 + (((hi * 2) ^ sw) << 4), a1 = r32 * 64 + (((hi * 2 + 1) ^ sw) << 4);
; #pragma unroll
;   for (int d0 = 0; d0 < 4; ++d0) {
;     const v8i32 vf = cat8(*reinterpret_cast<const v4i32*>(Vt + d0 * 2048 + a0), *reinterpret_cast<const v4i32*>(Vt + d0 * 2048 + a1));
;     o[d0] = __builtin_amdgcn_mfma_scale_f32_32x32x64_f8f6f4(p8, vf, o[d0], 0, 0, 0, 127, 0, 127); }
; }
; __device__ __forceinline__ void qkt9(f32x16& p0, f32x16& p1, const char* Kn, const char* Kr, const v8i32* qf, const float init, int r32, int hi) {
; #pragma unroll
;   for (int r = 0; r < 16; ++r) { p0[r] = init; p1[r] = init; }
; #pragma unroll
;   for (int s = 0; s < 2; ++s) { const int c0 = s * 4 + hi * 2;
;     const v8i32 a0 = cat8(*reinterpret_cast<const v4i32*>(Kn + KN8SW(r32, c0)), *reinterpret_cast<const v4i32*>(Kn + KN8SW(r32, c0 + 1)));
;     const v8i32 a1 = cat8(*reinterpret_cast<const v4i32*>(Kn + 4096 + KN8SW(r32, c0)), *reinterpret_cast<const v4i32*>(Kn + 4096 + KN8SW(r32, c0 + 1)));
;     p0 = __builtin_amdgcn_mfma_scale_f32_32x32x64_f8f6f4(a0, qf[s], p0, 0, 0, 0, 127, 0, 124);
;     p1 = __builtin_amdgcn_mfma_scale_f32_32x32x64_f8f6f4(a1, qf[s], p1, 0, 0, 0, 127, 0, 124); }
;   { const int c0 = hi * 2;
.Lmla_p0_cont:
	ds_read_b128 v[82:85], v215 offset:51200
	ds_read_b128 v[86:89], v216 offset:51200
	ds_read_b128 v[222:225], v215 offset:55296
	ds_read_b128 v[226:229], v216 offset:55296
	s_add_i32 m0, s98, 0x0
	s_nop 0
	global_load_lds_dwordx4 v176, s[18:19]
	s_add_i32 m0, s98, 0x4000
	s_nop 0
	global_load_lds_dwordx4 v178, s[16:17]
	s_add_i32 m0, s98, 0x8000
	s_nop 0
	global_load_lds_dwordx4 v[180:181], off
	v_exp_f32_e32 v0, v114
	v_exp_f32_e32 v177, v115
	v_exp_f32_e32 v179, v116
	v_exp_f32_e32 v254, v117
	v_add_f32_e32 v219, v0, v177
	v_cvt_pk_fp8_f32 v246, v0, v177
	v_add_f32_e32 v219, v179, v219
	v_add_f32_e32 v219, v254, v219
	v_cvt_pk_fp8_f32 v246, v179, v254 op_sel:[0,0,1]
	s_waitcnt lgkmcnt(2)
	v_mfma_scale_f32_32x32x64_f8f6f4 v[82:97], v[82:89], v[146:153], v[230:245], v194, v193 op_sel_hi:[0,0,0]
	v_exp_f32_e32 v0, v118
	v_exp_f32_e32 v177, v119
	v_exp_f32_e32 v179, v120
	v_exp_f32_e32 v254, v121
	v_add_f32_e32 v219, v0, v219
	v_add_f32_e32 v219, v177, v219
	v_cvt_pk_fp8_f32 v247, v0, v177
	v_add_f32_e32 v219, v179, v219
	v_add_f32_e32 v219, v254, v219
	v_cvt_pk_fp8_f32 v247, v179, v254 op_sel:[0,0,1]
	ds_read_b128 v[114:117], v213 offset:51200
	ds_read_b128 v[118:121], v214 offset:51200
	s_waitcnt lgkmcnt(2)
	v_mfma_scale_f32_32x32x64_f8f6f4 v[66:81], v[222:229], v[146:153], v[230:245], v194, v193 op_sel_hi:[0,0,0]
	ds_read_b128 v[222:225], v213 offset:55296
	ds_read_b128 v[226:229], v214 offset:55296
	v_exp_f32_e32 v0, v122
	v_exp_f32_e32 v177, v123
	v_exp_f32_e32 v179, v124
	v_exp_f32_e32 v254, v125
	v_add_f32_e32 v219, v0, v219
	v_add_f32_e32 v219, v177, v219
	v_cvt_pk_fp8_f32 v248, v0, v177
	v_add_f32_e32 v219, v179, v219
	v_add_f32_e32 v219, v254, v219
	v_cvt_pk_fp8_f32 v248, v179, v254 op_sel:[0,0,1]
	v_exp_f32_e32 v0, v126
	v_exp_f32_e32 v177, v127
	v_exp_f32_e32 v179, v128
	v_exp_f32_e32 v254, v129
	v_add_f32_e32 v219, v0, v219
	v_add_f32_e32 v219, v177, v219
	v_cvt_pk_fp8_f32 v249, v0, v177
	v_add_f32_e32 v219, v179, v219
	v_add_f32_e32 v219, v254, v219
	v_cvt_pk_fp8_f32 v249, v179, v254 op_sel:[0,0,1]
	ds_read_b128 v[122:125], v185 offset:59392
	ds_read_b128 v[126:129], v186 offset:59392
	s_waitcnt lgkmcnt(4)
	v_mfma_scale_f32_32x32x64_f8f6f4 v[82:97], v[114:121], v[138:145], v[82:97], v194, v193 op_sel_hi:[0,0,0]
	v_exp_f32_e32 v0, v98
	v_exp_f32_e32 v177, v99
	v_exp_f32_e32 v179, v100
	v_exp_f32_e32 v254, v101
	v_add_f32_e32 v219, v0, v219
	v_add_f32_e32 v219, v177, v219
	v_cvt_pk_fp8_f32 v250, v0, v177
	v_add_f32_e32 v219, v179, v219
	v_add_f32_e32 v219, v254, v219
	v_cvt_pk_fp8_f32 v250, v179, v254 op_sel:[0,0,1]
	s_waitcnt lgkmcnt(2)
	v_mfma_scale_f32_32x32x64_f8f6f4 v[66:81], v[222:229], v[138:145], v[66:81], v194, v193 op_sel_hi:[0,0,0]
	ds_read_b128 v[222:225], v185 offset:61440
	ds_read_b128 v[226:229], v186 offset:61440
	v_exp_f32_e32 v0, v102
	v_exp_f32_e32 v177, v103
	v_exp_f32_e32 v179, v104
	v_exp_f32_e32 v254, v105
	v_add_f32_e32 v219, v0, v219
	v_add_f32_e32 v219, v177, v219
	v_cvt_pk_fp8_f32 v251, v0, v177
	v_add_f32_e32 v219, v179, v219
	v_add_f32_e32 v219, v254, v219
	v_cvt_pk_fp8_f32 v251, v179, v254 op_sel:[0,0,1]
	v_exp_f32_e32 v0, v106
	v_exp_f32_e32 v177, v107
	v_exp_f32_e32 v179, v108
	v_exp_f32_e32 v254, v109
	v_add_f32_e32 v219, v0, v219
	v_add_f32_e32 v219, v177, v219
	v_cvt_pk_fp8_f32 v252, v0, v177
	v_add_f32_e32 v219, v179, v219
	v_add_f32_e32 v219, v254, v219
	v_cvt_pk_fp8_f32 v252, v179, v254 op_sel:[0,0,1]
	s_waitcnt lgkmcnt(2)
	v_mfma_scale_f32_32x32x64_f8f6f4 v[82:97], v[122:129], v[130:137], v[82:97], v194, v193 op_sel_hi:[0,0,0]
	v_exp_f32_e32 v0, v110
	v_exp_f32_e32 v177, v111
	v_exp_f32_e32 v179, v112
	v_exp_f32_e32 v254, v113
	v_add_f32_e32 v219, v0, v219
	v_add_f32_e32 v219, v177, v219
	v_cvt_pk_fp8_f32 v253, v0, v177
	v_add_f32_e32 v219, v179, v219
	v_add_f32_e32 v219, v254, v219
	v_cvt_pk_fp8_f32 v253, v179, v254 op_sel:[0,0,1]
	ds_read_b128 v[122:125], v185 offset:8192
	ds_read_b128 v[126:129], v186 offset:8192
	ds_read_b128 v[114:117], v185 offset:10240
	ds_read_b128 v[118:121], v186 offset:10240
	ds_read_b128 v[106:109], v185 offset:12288
	ds_read_b128 v[110:113], v186 offset:12288
	ds_read_b128 v[98:101], v185 offset:14336
	ds_read_b128 v[102:105], v186 offset:14336
	s_waitcnt lgkmcnt(8)
	v_mfma_scale_f32_32x32x64_f8f6f4 v[66:81], v[222:229], v[130:137], v[66:81], v194, v193 op_sel_hi:[0,0,0]
	v_mov_b32_e32 v0, v219
	s_nop 1
	v_permlane32_swap_b32_e32 v219, v0
	v_add_f32_e32 v219, v219, v0
	v_fma_f32 v209, v209, v221, v219
	v_add_u32_e32 v176, 0x2000, v176
	v_add_u32_e32 v178, 0x20000, v178
	s_mov_b64 s[20:21], 0x1000
	v_lshl_add_u64 v[180:181], v[180:181], 0, s[20:21]
	v_max_f32_e32 v177, v82, v83
	v_max3_f32 v177, v177, v84, v85
	v_max3_f32 v177, v177, v86, v87
	v_max3_f32 v177, v177, v88, v89
	v_max3_f32 v177, v177, v90, v91
	v_max3_f32 v177, v177, v92, v93
	v_max3_f32 v177, v177, v94, v95
	v_max3_f32 v177, v177, v96, v97
	s_waitcnt lgkmcnt(6)
	v_mfma_scale_f32_32x32x64_f8f6f4 v[50:65], v[246:253], v[122:129], v[50:65], v194, v194 op_sel_hi:[0,0,0]
	v_max_f32_e32 v0, v66, v67
	v_max3_f32 v0, v0, v68, v69
	v_max3_f32 v0, v0, v70, v71
	s_waitcnt lgkmcnt(4)
	v_mfma_scale_f32_32x32x64_f8f6f4 v[34:49], v[246:253], v[114:121], v[34:49], v194, v194 op_sel_hi:[0,0,0]
	v_max3_f32 v0, v0, v72, v73
	v_max3_f32 v0, v0, v74, v75
	v_max3_f32 v0, v0, v76, v77
	s_waitcnt lgkmcnt(2)
	v_mfma_scale_f32_32x32x64_f8f6f4 v[18:33], v[246:253], v[106:113], v[18:33], v194, v194 op_sel_hi:[0,0,0]
	v_max3_f32 v0, v0, v78, v79
	v_max3_f32 v0, v0, v80, v81
	v_max_f32_e32 v177, v177, v0
	v_mov_b32_e32 v0, v177
	v_mov_b32_e32 v218, 1.0
	s_waitcnt lgkmcnt(0)
	v_mfma_scale_f32_32x32x64_f8f6f4 v[2:17], v[246:253], v[98:105], v[2:17], v194, v194 op_sel_hi:[0,0,0]
	s_waitcnt vmcnt(0)
	s_waitcnt lgkmcnt(0)
	s_barrier
	v_permlane32_swap_b32_e32 v177, v0
	v_max_f32_e32 v177, v177, v0
	v_cmp_ge_f32_e32 vcc, s90, v177
	s_cmp_eq_u64 vcc, exec
	s_cbranch_scc0 .Lmla_p1_newmax
.Lmla_p1_cont:
	v_mov_b32_e32 v0, v218
	s_setprio 0
	s_branch .LBB0_1343

; __device__ __forceinline__ void finishSM9(f32x16& p0, f32x16& p1, float alpha, float& l_reg, v8i32& p8) {
; #pragma unroll
;   for (int r = 0; r < 16; ++r) { p0[r] = __builtin_amdgcn_exp2f(p0[r]); p1[r] = __builtin_amdgcn_exp2f(p1[r]); }
;   float ps = 0;
; #pragma unroll
;   for (int r = 0; r < 16; ++r) ps += p0[r];
; #pragma unroll
;   for (int r = 0; r < 16; ++r) ps += p1[r];
;   { auto rr = __builtin_amdgcn_permlane32_swap(__float_as_uint(ps), __float_as_uint(ps), false, false);
;     ps = __uint_as_float(rr[0]) + __uint_as_float(rr[1]); }
;   l_reg = l_reg * alpha + ps;
; #pragma unroll
;   for (int g = 0; g < 4; ++g) {
;     int w = __builtin_amdgcn_cvt_pk_fp8_f32(p0[4 * g], p0[4 * g + 1], 0, false); p8[g] = __builtin_amdgcn_cvt_pk_fp8_f32(p0[4 * g + 2], p0[4 * g + 3], w, true);
;     int u = __builtin_amdgcn_cvt_pk_fp8_f32(p1[4 * g], p1[4 * g + 1], 0, false); p8[4 + g] = __builtin_amdgcn_cvt_pk_fp8_f32(p1[4 * g + 2], p1[4 * g + 3], u, true); }
; }
; __device__ __forceinline__ void pv8(f32x16* o, const char* Vt, const v8i32 p8, int r32, int hi) {
;   const int sw = (r32 >> 2) & 3, a0 = r32 * 64 + (((hi * 2) ^ sw) << 4), a1 = r32 * 64 + (((hi * 2 + 1) ^ sw) << 4);
; #pragma unroll
;   for (int d0 = 0; d0 < 4; ++d0) {
;     const v8i32 vf = cat8(*reinterpret_cast<const v4i32*>(Vt + d0 * 2048 + a0), *reinterpret_cast<const v4i32*>(Vt + d0 * 2048 + a1));
;     o[d0] = __builtin_amdgcn_mfma_scale_f32_32x32x64_f8f6f4(p8, vf, o[d0], 0, 0, 0, 127, 0, 127); }
; }
; __device__ __forceinline__ void qkt9(f32x16& p0, f32x16& p1, const char* Kn, const char* Kr, const v8i32* qf, const float init, int r32, int hi) {
; #pragma unroll
;   for (int r = 0; r < 16; ++r) { p0[r] = init; p1[r] = init; }
; #pragma unroll
;   for (int s = 0; s < 2; ++s) { const int c0 = s * 4 + hi * 2;
;     const v8i32 a0 = cat8(*reinterpret_cast<const v4i32*>(Kn + KN8SW(r32, c0)), *reinterpret_cast<const v4i32*>(Kn + KN8SW(r32, c0 + 1)));
;     const v8i32 a1 = cat8(*reinterpret_cast<const v4i32*>(Kn + 4096 + KN8SW(r32, c0)), *reinterpret_cast<const v4i32*>(Kn + 4096 + KN8SW(r32, c0 + 1)));
;     p0 = __builtin_amdgcn_mfma_scale_f32_32x32x64_f8f6f4(a0, qf[s], p0, 0, 0, 0, 127, 0, 124);
;     p1 = __builtin_amdgcn_mfma_scale_f32_32x32x64_f8f6f4(a1, qf[s], p1, 0, 0, 0, 127, 0, 124); }
;   { const int c0 = hi * 2;
.Lmla_q0_cont:
	ds_read_b128 v[82:85], v215 offset:51200
	ds_read_b128 v[86:89], v216 offset:51200
	ds_read_b128 v[222:225], v215 offset:55296
	ds_read_b128 v[226:229], v216 offset:55296
	v_exp_f32_e32 v0, v114
	v_exp_f32_e32 v177, v115
	v_exp_f32_e32 v179, v116
	v_exp_f32_e32 v254, v117
	v_add_f32_e32 v219, v0, v177
	v_cvt_pk_fp8_f32 v246, v0, v177
	v_add_f32_e32 v219, v179, v219
	v_add_f32_e32 v219, v254, v219
	v_cvt_pk_fp8_f32 v246, v179, v254 op_sel:[0,0,1]
	s_waitcnt lgkmcnt(2)
	v_mfma_scale_f32_32x32x64_f8f6f4 v[82:97], v[82:89], v[146:153], v[230:245], v194, v193 op_sel_hi:[0,0,0]
	v_exp_f32_e32 v0, v118
	v_exp_f32_e32 v177, v119
	v_exp_f32_e32 v179, v120
	v_exp_f32_e32 v254, v121
	v_add_f32_e32 v219, v0, v219
	v_add_f32_e32 v219, v177, v219
	v_cvt_pk_fp8_f32 v247, v0, v177
	v_add_f32_e32 v219, v179, v219
	v_add_f32_e32 v219, v254, v219
	v_cvt_pk_fp8_f32 v247, v179, v254 op_sel:[0,0,1]
	ds_read_b128 v[114:117], v213 offset:51200
	ds_read_b128 v[118:121], v214 offset:51200
	s_waitcnt lgkmcnt(2)
	v_mfma_scale_f32_32x32x64_f8f6f4 v[66:81], v[222:229], v[146:153], v[230:245], v194, v193 op_sel_hi:[0,0,0]
	ds_read_b128 v[222:225], v213 offset:55296
	ds_read_b128 v[226:229], v214 offset:55296
	v_exp_f32_e32 v0, v122
	v_exp_f32_e32 v177, v123
	v_exp_f32_e32 v179, v124
	v_exp_f32_e32 v254, v125
	v_add_f32_e32 v219, v0, v219
	v_add_f32_e32 v219, v177, v219
	v_cvt_pk_fp8_f32 v248, v0, v177
	v_add_f32_e32 v219, v179, v219
	v_add_f32_e32 v219, v254, v219
	v_cvt_pk_fp8_f32 v248, v179, v254 op_sel:[0,0,1]
	v_exp_f32_e32 v0, v126
	v_exp_f32_e32 v177, v127
	v_exp_f32_e32 v179, v128
	v_exp_f32_e32 v254, v129
	v_add_f32_e32 v219, v0, v219
	v_add_f32_e32 v219, v177, v219
	v_cvt_pk_fp8_f32 v249, v0, v177
	v_add_f32_e32 v219, v179, v219
	v_add_f32_e32 v219, v254, v219
	v_cvt_pk_fp8_f32 v249, v179, v254 op_sel:[0,0,1]
	ds_read_b128 v[122:125], v185 offset:59392
	ds_read_b128 v[126:129], v186 offset:59392
	s_waitcnt lgkmcnt(4)
	v_mfma_scale_f32_32x32x64_f8f6f4 v[82:97], v[114:121], v[138:145], v[82:97], v194, v193 op_sel_hi:[0,0,0]
	v_exp_f32_e32 v0, v98
	v_exp_f32_e32 v177, v99
	v_exp_f32_e32 v179, v100
	v_exp_f32_e32 v254, v101
	v_add_f32_e32 v219, v0, v219
	v_add_f32_e32 v219, v177, v219
	v_cvt_pk_fp8_f32 v250, v0, v177
	v_add_f32_e32 v219, v179, v219
	v_add_f32_e32 v219, v254, v219
	v_cvt_pk_fp8_f32 v250, v179, v254 op_sel:[0,0,1]
	s_waitcnt lgkmcnt(2)
	v_mfma_scale_f32_32x32x64_f8f6f4 v[66:81], v[222:229], v[138:145], v[66:81], v194, v193 op_sel_hi:[0,0,0]
	ds_read_b128 v[222:225], v185 offset:61440
	ds_read_b128 v[226:229], v186 offset:61440
	v_exp_f32_e32 v0, v102
	v_exp_f32_e32 v177, v103
	v_exp_f32_e32 v179, v104
	v_exp_f32_e32 v254, v105
	v_add_f32_e32 v219, v0, v219
	v_add_f32_e32 v219, v177, v219
	v_cvt_pk_fp8_f32 v251, v0, v177
	v_add_f32_e32 v219, v179, v219
	v_add_f32_e32 v219, v254, v219
	v_cvt_pk_fp8_f32 v251, v179, v254 op_sel:[0,0,1]
	v_exp_f32_e32 v0, v106
	v_exp_f32_e32 v177, v107
	v_exp_f32_e32 v179, v108
	v_exp_f32_e32 v254, v109
	v_add_f32_e32 v219, v0, v219
	v_add_f32_e32 v219, v177, v219
	v_cvt_pk_fp8_f32 v252, v0, v177
	v_add_f32_e32 v219, v179, v219
	v_add_f32_e32 v219, v254, v219
	v_cvt_pk_fp8_f32 v252, v179, v254 op_sel:[0,0,1]
	s_waitcnt lgkmcnt(2)
	v_mfma_scale_f32_32x32x64_f8f6f4 v[82:97], v[122:129], v[130:137], v[82:97], v194, v193 op_sel_hi:[0,0,0]
	v_exp_f32_e32 v0, v110
	v_exp_f32_e32 v177, v111
	v_exp_f32_e32 v179, v112
	v_exp_f32_e32 v254, v113
	v_add_f32_e32 v219, v0, v219
	v_add_f32_e32 v219, v177, v219
	v_cvt_pk_fp8_f32 v253, v0, v177
	v_add_f32_e32 v219, v179, v219
	v_add_f32_e32 v219, v254, v219
	v_cvt_pk_fp8_f32 v253, v179, v254 op_sel:[0,0,1]
	ds_read_b128 v[122:125], v185 offset:8192
	ds_read_b128 v[126:129], v186 offset:8192
	ds_read_b128 v[114:117], v185 offset:10240
	ds_read_b128 v[118:121], v186 offset:10240
	ds_read_b128 v[106:109], v185 offset:12288
	ds_read_b128 v[110:113], v186 offset:12288
	ds_read_b128 v[98:101], v185 offset:14336
	ds_read_b128 v[102:105], v186 offset:14336
	s_waitcnt lgkmcnt(8)
	v_mfma_scale_f32_32x32x64_f8f6f4 v[66:81], v[222:229], v[130:137], v[66:81], v194, v193 op_sel_hi:[0,0,0]
	v_mov_b32_e32 v0, v219
	s_nop 1
	v_permlane32_swap_b32_e32 v219, v0
	v_add_f32_e32 v219, v219, v0
	v_fma_f32 v209, v209, v221, v219
	v_max_f32_e32 v177, v82, v83
	v_max3_f32 v177, v177, v84, v85
	v_max3_f32 v177, v177, v86, v87
	v_max3_f32 v177, v177, v88, v89
	v_max3_f32 v177, v177, v90, v91
	v_max3_f32 v177, v177, v92, v93
	v_max3_f32 v177, v177, v94, v95
	v_max3_f32 v177, v177, v96, v97
	s_waitcnt lgkmcnt(6)
	v_mfma_scale_f32_32x32x64_f8f6f4 v[50:65], v[246:253], v[122:129], v[50:65], v194, v194 op_sel_hi:[0,0,0]
	s_waitcnt lgkmcnt(4)
	v_mfma_scale_f32_32x32x64_f8f6f4 v[34:49], v[246:253], v[114:121], v[34:49], v194, v194 op_sel_hi:[0,0,0]
	s_waitcnt vmcnt(0)
	s_waitcnt lgkmcnt(0)
	s_barrier
	v_max_f32_e32 v0, v66, v67
	v_max3_f32 v0, v0, v68, v69
	v_max3_f32 v0, v0, v70, v71
	v_max3_f32 v0, v0, v72, v73
	s_waitcnt lgkmcnt(2)
	v_mfma_scale_f32_32x32x64_f8f6f4 v[18:33], v[246:253], v[106:113], v[18:33], v194, v194 op_sel_hi:[0,0,0]
	v_max3_f32 v0, v0, v74, v75
	v_max3_f32 v0, v0, v76, v77
	v_max3_f32 v0, v0, v78, v79
	v_max3_f32 v0, v0, v80, v81
	s_waitcnt lgkmcnt(0)
	v_mfma_scale_f32_32x32x64_f8f6f4 v[2:17], v[246:253], v[98:105], v[2:17], v194, v194 op_sel_hi:[0,0,0]
	v_max_f32_e32 v177, v177, v0
	v_mov_b32_e32 v0, v177
	v_mov_b32_e32 v218, 1.0
	s_nop 0
	v_permlane32_swap_b32_e32 v177, v0
	v_max_f32_e32 v177, v177, v0
	v_cmp_ge_f32_e32 vcc, s90, v177
	s_cmp_eq_u64 vcc, exec
	s_cbranch_scc0 .Lmla_q1_newmax
.Lmla_q1_cont:
	v_mov_b32_e32 v0, v218
	s_branch .LBB0_1343
